# attention loops: back edge rotated (v_mov + s_cbranch_vccz top; s_branch exit)
# speedup vs baseline: 1.0065x; 1.0065x over previous
; #define SBAR() __builtin_amdgcn_sched_barrier(0)
; #define KWRITE(b, src0, src1) do { if constexpr (ND0 == 4) { *(bf16x8*)(K_lds + (b) * SHM_K + KSWZ(kr, kcb)) = src0; } \
;     else { int kc = sc * 2; *(bf16x8*)(K_lds + (b) * SHM_K + KSWZ(sr, kc)) = src0; *(bf16x8*)(K_lds + (b) * SHM_K + KSWZ(32 + sr, kc)) = src1; } } while (0)
; #define SLOAD_A(k0) do { vs0a = *reinterpret_cast<const bf16x8*>(&Vh[(long)((k0) + sr) * LDK + sc]); vs1a = *reinterpret_cast<const bf16x8*>(&Vh[(long)((k0) + 32 + sr) * LDK + sc]); KLOAD(ks0a, ks1a, k0); } while (0)
; #define SLOAD_B(k0) do { vs0b = *reinterpret_cast<const bf16x8*>(&Vh[(long)((k0) + sr) * LDK + sc]); vs1b = *reinterpret_cast<const bf16x8*>(&Vh[(long)((k0) + 32 + sr) * LDK + sc]); KLOAD(ks0b, ks1b, k0); } while (0)
; #define VWRITE_A(b) do { *(bf16x8*)(V_lds + (b) * SHM_V + vst0) = vs0a; *(bf16x8*)(V_lds + (b) * SHM_V + vst1) = vs1a; } while (0)
; #define VWRITE_B(b) do { *(bf16x8*)(V_lds + (b) * SHM_V + vst0) = vs0b; *(bf16x8*)(V_lds + (b) * SHM_V + vst1) = vs1b; } while (0)
; #define SWAIT() do { if constexpr (ND0 == 4) asm volatile("s_waitcnt vmcnt(3)" ::: "memory"); else asm volatile("s_waitcnt vmcnt(4)" ::: "memory"); } while (0)
; #define PSM(P0, P1, MN, AL) do { if constexpr (PRE) partialSM_pre(P0, P1, m_reg, AL, 11.541560327111707f); else partialSM(P0, P1, m_reg, MN, AL, C, thr_raw); } while (0)
; __device__ __forceinline__ void partialSM_pre(f32x16& p0, f32x16& p1, float& m_ref, float& alpha, const float thr2) {
;     ...
; #pragma unroll
;   for (int r = 0; r < 16; ++r) p0[r] = __builtin_amdgcn_exp2f(p0[r]);
; template <int ND0, int LDQ, int LDK, int LDO> ...
;     ...
;   for (int j = 1; j + 1 < NT; j += 2) {
;     SBAR(); qkt<ND0>(pB0, pB1, Kq1, qr, r32, hi);
;     finishSM(pA0, pA1, alA, l_reg, pa0, pa1, pa2, pa3); SBAR();
;     SLOAD_B((j + 2) * KVBLK); SBAR();
;     pv_d0(o, vb0, pa0, pa1, pa2, pa3); KWRITE(0, ks0a, ks1a); PSM(pB0, pB1, mnB, alB);
;     __syncthreads(); SWAIT(); VWRITE_A(0);
;     RESC(alB); __syncthreads();
;     SBAR(); qkt<ND0>(pA0, pA1, Kq0, qr, r32, hi);
;     finishSM(pB0, pB1, alB, l_reg, pa0, pa1, pa2, pa3); SBAR();
;     if (j + 3 < NT) SLOAD_A((j + 3) * KVBLK); SBAR();
;     pv_d0(o, vb0 + (int)SHM_V, pa0, pa1, pa2, pa3); KWRITE(1, ks0b, ks1b); PSM(pA0, pA1, mnA, alA);
;     __syncthreads(); SWAIT(); VWRITE_B(1);
;     RESC(alA); __syncthreads();
;   }
.LBB0_161:
	v_lshl_add_u64 v[188:189], v[188:189], 0, s[42:43]
	s_and_b64 vcc, exec, s[4:5]
	v_exp_f32_e32 v163, v108
	v_exp_f32_e32 v165, v109
	v_exp_f32_e32 v162, v110
	v_exp_f32_e32 v164, v111
	v_exp_f32_e32 v167, v104
	v_exp_f32_e32 v169, v105
	v_exp_f32_e32 v166, v106
	v_exp_f32_e32 v168, v107
	v_mov_b32_e32 v207, v170
	s_cbranch_vccz .LBB0_146
	s_branch .LBB0_167

; #define SBAR() __builtin_amdgcn_sched_barrier(0)
; #define KWRITE(b, src0, src1) do { if constexpr (ND0 == 4) { *(bf16x8*)(K_lds + (b) * SHM_K + KSWZ(kr, kcb)) = src0; } \
;     else { int kc = sc * 2; *(bf16x8*)(K_lds + (b) * SHM_K + KSWZ(sr, kc)) = src0; *(bf16x8*)(K_lds + (b) * SHM_K + KSWZ(32 + sr, kc)) = src1; } } while (0)
; #define SLOAD_A(k0) do { vs0a = *reinterpret_cast<const bf16x8*>(&Vh[(long)((k0) + sr) * LDK + sc]); vs1a = *reinterpret_cast<const bf16x8*>(&Vh[(long)((k0) + 32 + sr) * LDK + sc]); KLOAD(ks0a, ks1a, k0); } while (0)
; #define SLOAD_B(k0) do { vs0b = *reinterpret_cast<const bf16x8*>(&Vh[(long)((k0) + sr) * LDK + sc]); vs1b = *reinterpret_cast<const bf16x8*>(&Vh[(long)((k0) + 32 + sr) * LDK + sc]); KLOAD(ks0b, ks1b, k0); } while (0)
; #define VWRITE_A(b) do { *(bf16x8*)(V_lds + (b) * SHM_V + vst0) = vs0a; *(bf16x8*)(V_lds + (b) * SHM_V + vst1) = vs1a; } while (0)
; #define VWRITE_B(b) do { *(bf16x8*)(V_lds + (b) * SHM_V + vst0) = vs0b; *(bf16x8*)(V_lds + (b) * SHM_V + vst1) = vs1b; } while (0)
; #define SWAIT() do { if constexpr (ND0 == 4) asm volatile("s_waitcnt vmcnt(3)" ::: "memory"); else asm volatile("s_waitcnt vmcnt(4)" ::: "memory"); } while (0)
; #define PSM(P0, P1, MN, AL) do { if constexpr (PRE) partialSM_pre(P0, P1, m_reg, AL, 11.541560327111707f); else partialSM(P0, P1, m_reg, MN, AL, C, thr_raw); } while (0)
; __device__ __forceinline__ void partialSM_pre(f32x16& p0, f32x16& p1, float& m_ref, float& alpha, const float thr2) {
;     ...
; #pragma unroll
;   for (int r = 0; r < 16; ++r) p0[r] = __builtin_amdgcn_exp2f(p0[r]);
; template <int ND0, int LDQ, int LDK, int LDO> ...
;     ...
;   for (int j = 1; j + 1 < NT; j += 2) {
;     SBAR(); qkt<ND0>(pB0, pB1, Kq1, qr, r32, hi);
;     finishSM(pA0, pA1, alA, l_reg, pa0, pa1, pa2, pa3); SBAR();
;     SLOAD_B((j + 2) * KVBLK); SBAR();
;     pv_d0(o, vb0, pa0, pa1, pa2, pa3); KWRITE(0, ks0a, ks1a); PSM(pB0, pB1, mnB, alB);
;     __syncthreads(); SWAIT(); VWRITE_A(0);
;     RESC(alB); __syncthreads();
;     SBAR(); qkt<ND0>(pA0, pA1, Kq0, qr, r32, hi);
;     finishSM(pB0, pB1, alB, l_reg, pa0, pa1, pa2, pa3); SBAR();
;     if (j + 3 < NT) SLOAD_A((j + 3) * KVBLK); SBAR();
;     pv_d0(o, vb0 + (int)SHM_V, pa0, pa1, pa2, pa3); KWRITE(1, ks0b, ks1b); PSM(pA0, pA1, mnA, alA);
;     __syncthreads(); SWAIT(); VWRITE_B(1);
;     RESC(alA); __syncthreads();
;   }
.LBB0_228:
	s_add_i32 s40, s40, 2
	s_and_b64 vcc, exec, s[18:19]
	v_exp_f32_e32 v143, v108
	v_exp_f32_e32 v142, v110
	v_exp_f32_e32 v144, v111
	v_exp_f32_e32 v145, v106
	v_exp_f32_e32 v147, v104
	v_exp_f32_e32 v149, v105
	v_exp_f32_e32 v148, v107
	v_exp_f32_e32 v146, v109
	v_mov_b32_e32 v200, v150
	s_cbranch_vccz .LBB0_214
	s_branch .LBB0_234
